# cmp_item row staging: nine loads in flight; lru_apply carry scan on scalar counters with 16-step load batches
# speedup vs baseline: 1.0075x; 1.0020x over previous
.LBB0_790:
	s_andn2_b64 vcc, exec, s[10:11]
	s_cbranch_vccnz .LBB0_551
	s_mul_hi_i32 s4, s91, 0x2aaaaaab
	s_lshr_b32 s5, s4, 31
	s_ashr_i32 s4, s4, 4
	s_add_i32 s4, s4, s5
	s_mul_i32 s5, s4, 0x60
	s_sub_i32 s5, s91, s5
	s_bfe_i32 s10, s5, 0x80000
	s_bfe_u32 s10, s10, 0x5000a
	s_add_i32 s10, s5, s10
	s_bfe_i32 s11, s10, 0x80000
	s_sext_i32_i16 s11, s11
	s_and_b32 s10, s10, 0xe0
	s_lshr_b32 s34, s11, 5
	s_sub_i32 s5, s5, s10
	s_addk_i32 s91, 0x5f
	s_cmpk_lt_u32 s91, 0xbf
	v_mov_b32_e32 v4, v203
	s_cselect_b64 s[26:27], -1, 0
	s_cmpk_gt_u32 s91, 0xbe
	s_movk_i32 s12, 0x1080
	s_sext_i32_i8 s5, s5
	v_readfirstlane_b32 s35, v4
	s_cselect_b64 s[10:11], -1, 0
	v_cmp_gt_i32_e32 vcc, s12, v4
	s_and_saveexec_b64 s[28:29], vcc
	s_cbranch_execz .LBB0_794
	s_and_b64 s[12:13], s[26:27], exec
	s_movk_i32 s12, 0x3c00
	s_cselect_b32 s12, s12, 0x3d80
	s_add_u32 s18, s14, s12
	s_sext_i32_i8 s12, s34
	s_addc_u32 s19, s15, 0
	s_lshl_b32 s12, s12, 6
	s_ashr_i32 s13, s12, 31
	s_lshl_b64 s[12:13], s[12:13], 1
	s_add_u32 s18, s18, s12
	v_lshlrev_b32_e32 v0, 4, v4
	s_addc_u32 s19, s19, s13
	v_and_b32_e32 v0, 0x70, v0
	s_lshl_b32 s12, s5, 9
	v_lshl_add_u64 v[2:3], s[18:19], 0, v[0:1]
	v_add_u32_e32 v0, 0, v0
	s_mov_b64 s[30:31], 0
	v_mov_b32_e32 v5, v4
	v_ashrrev_i32_e32 v10, 3, v4
	v_add_u32_e32 v6, s12, v10
	v_cmp_gt_u32_e32 vcc, 0x80, v4
	v_add_u32_e32 v7, 0x200, v6
	v_min_i32_e32 v7, 0x3fff, v7
	s_and_saveexec_b64 s[30:31], vcc
	s_cbranch_execz .Lcmp_stage_a
	v_mad_i64_i32 v[44:45], s[18:19], v7, s63, v[2:3]
	global_load_dwordx4 v[44:47], v[44:45], off
.Lcmp_stage_a:
	s_mov_b64 exec, s[30:31]
	v_min_i32_e32 v7, 0x3fff, v6
	v_mad_i64_i32 v[12:13], s[18:19], v7, s63, v[2:3]
	global_load_dwordx4 v[12:15], v[12:13], off
	v_add_u32_e32 v7, 64, v6
	v_min_i32_e32 v7, 0x3fff, v7
	v_mad_i64_i32 v[16:17], s[18:19], v7, s63, v[2:3]
	global_load_dwordx4 v[16:19], v[16:17], off
	v_add_u32_e32 v7, 0x80, v6
	v_min_i32_e32 v7, 0x3fff, v7
	v_mad_i64_i32 v[20:21], s[18:19], v7, s63, v[2:3]
	global_load_dwordx4 v[20:23], v[20:21], off
	v_add_u32_e32 v7, 0xc0, v6
	v_min_i32_e32 v7, 0x3fff, v7
	v_mad_i64_i32 v[24:25], s[18:19], v7, s63, v[2:3]
	global_load_dwordx4 v[24:27], v[24:25], off
	v_add_u32_e32 v7, 0x100, v6
	v_min_i32_e32 v7, 0x3fff, v7
	v_mad_i64_i32 v[28:29], s[18:19], v7, s63, v[2:3]
	global_load_dwordx4 v[28:31], v[28:29], off
	v_add_u32_e32 v7, 0x140, v6
	v_min_i32_e32 v7, 0x3fff, v7
	v_mad_i64_i32 v[32:33], s[18:19], v7, s63, v[2:3]
	global_load_dwordx4 v[32:35], v[32:33], off
	v_add_u32_e32 v7, 0x180, v6
	v_min_i32_e32 v7, 0x3fff, v7
	v_mad_i64_i32 v[36:37], s[18:19], v7, s63, v[2:3]
	global_load_dwordx4 v[36:39], v[36:37], off
	v_add_u32_e32 v7, 0x1c0, v6
	v_min_i32_e32 v7, 0x3fff, v7
	v_mad_i64_i32 v[40:41], s[18:19], v7, s63, v[2:3]
	global_load_dwordx4 v[40:43], v[40:41], off
	v_ashrrev_i32_e32 v11, 7, v4
	v_and_b32_e32 v10, 15, v10
	v_mad_u32_u24 v10, v10, 34, v11
	v_mad_u64_u32 v[10:11], s[18:19], v10, s0, v[0:1]
	s_waitcnt vmcnt(7)
	ds_write_b128 v10, v[12:15]
	s_waitcnt vmcnt(6)
	ds_write_b128 v10, v[16:19] offset:576
	s_waitcnt vmcnt(5)
	ds_write_b128 v10, v[20:23] offset:1152
	s_waitcnt vmcnt(4)
	ds_write_b128 v10, v[24:27] offset:1728
	s_waitcnt vmcnt(3)
	ds_write_b128 v10, v[28:31] offset:2304
	s_waitcnt vmcnt(2)
	ds_write_b128 v10, v[32:35] offset:2880
	s_waitcnt vmcnt(1)
	ds_write_b128 v10, v[36:39] offset:3456
	s_waitcnt vmcnt(0)
	ds_write_b128 v10, v[40:43] offset:4032
	s_and_saveexec_b64 s[30:31], vcc
	s_cbranch_execz .Lcmp_stage_b
	ds_write_b128 v10, v[44:47] offset:4608
.Lcmp_stage_b:
	s_mov_b64 exec, s[30:31]

.LBB0_1256:
	s_andn2_b64 vcc, exec, s[6:7]
	s_cbranch_vccnz .LBB0_855
	s_mul_hi_i32 s6, s24, 0x2aaaaaab
	s_lshr_b32 s7, s6, 31
	s_add_i32 s6, s6, s7
	s_mul_i32 s7, s6, 6
	v_mov_b32_e32 v2, v203
	s_sub_i32 s7, s24, s7
	s_lshl_b32 s30, s7, 7
	s_lshl_b32 s7, s6, 4
	v_ashrrev_i32_e32 v0, 7, v2
	v_mul_lo_u32 v0, v0, s7
	v_ashrrev_i32_e32 v6, 2, v0
	v_add_u32_e32 v0, s7, v0
	v_ashrrev_i32_e32 v3, 2, v0
	s_ashr_i32 s31, s30, 31
	v_cmp_lt_i32_e32 vcc, v6, v3
	v_mov_b32_e32 v20, 0
	v_mov_b32_e32 v21, 1.0
	s_and_saveexec_b64 s[28:29], vcc
	s_cbranch_execz .LBB0_1267
	s_nop 0
	v_readfirstlane_b32 s10, v6
	s_mul_i32 s10, s10, 0xc00
	s_lshl_b32 s11, s30, 2
	s_add_u32 s36, s66, 0x1c8400
	s_addc_u32 s37, s67, 0
	s_add_u32 s36, s36, s10
	s_addc_u32 s37, s37, 0
	s_add_u32 s36, s36, s11
	s_addc_u32 s37, s37, 0
	s_add_u32 s38, s36, 0xc0000
	s_addc_u32 s39, s37, 0
	v_and_b32_e32 v0, 0x7f, v2
	v_lshlrev_b32_e32 v40, 2, v0
	v_mov_b32_e32 v21, 1.0
	v_mov_b32_e32 v20, 0
	s_lshr_b32 s12, s7, 2
	s_bfe_u32 s34, s12, 0x20002
	s_lshr_b32 s12, s12, 4
	s_cmp_eq_u32 s34, 0
	s_cbranch_scc1 .Llru_scan_main
.Llru_scan_rem:
	global_load_dword v4, v40, s[36:37]
	global_load_dword v24, v40, s[38:39]
	global_load_dword v5, v40, s[36:37] offset:3072
	global_load_dword v25, v40, s[38:39] offset:3072
	s_add_u32 s36, s36, 0x1800
	s_addc_u32 s37, s37, 0
	s_add_u32 s38, s38, 0x1800
	s_addc_u32 s39, s39, 0
	global_load_dword v6, v40, s[36:37]
	global_load_dword v26, v40, s[38:39]
	global_load_dword v7, v40, s[36:37] offset:3072
	global_load_dword v27, v40, s[38:39] offset:3072
	s_add_u32 s36, s36, 0x1800
	s_addc_u32 s37, s37, 0
	s_add_u32 s38, s38, 0x1800
	s_addc_u32 s39, s39, 0
	s_waitcnt vmcnt(6)
	v_mul_f32_e32 v21, v21, v4
	v_fma_f32 v20, v20, v4, v24
	s_waitcnt vmcnt(4)
	v_mul_f32_e32 v21, v21, v5
	v_fma_f32 v20, v20, v5, v25
	s_waitcnt vmcnt(2)
	v_mul_f32_e32 v21, v21, v6
	v_fma_f32 v20, v20, v6, v26
	s_waitcnt vmcnt(0)
	v_mul_f32_e32 v21, v21, v7
	v_fma_f32 v20, v20, v7, v27
	s_sub_i32 s34, s34, 1
	s_cmp_lg_u32 s34, 0
	s_cbranch_scc1 .Llru_scan_rem
.Llru_scan_main:
	s_cmp_eq_u32 s12, 0
	s_cbranch_scc1 .Llru_scan_done
.Llru_scan_16:
	global_load_dword v4, v40, s[36:37]
	global_load_dword v24, v40, s[38:39]
	global_load_dword v5, v40, s[36:37] offset:3072
	global_load_dword v25, v40, s[38:39] offset:3072
	s_add_u32 s36, s36, 0x1800
	s_addc_u32 s37, s37, 0
	s_add_u32 s38, s38, 0x1800
	s_addc_u32 s39, s39, 0
	global_load_dword v6, v40, s[36:37]
	global_load_dword v26, v40, s[38:39]
	global_load_dword v7, v40, s[36:37] offset:3072
	global_load_dword v27, v40, s[38:39] offset:3072
	s_add_u32 s36, s36, 0x1800
	s_addc_u32 s37, s37, 0
	s_add_u32 s38, s38, 0x1800
	s_addc_u32 s39, s39, 0
	global_load_dword v8, v40, s[36:37]
	global_load_dword v28, v40, s[38:39]
	global_load_dword v9, v40, s[36:37] offset:3072
	global_load_dword v29, v40, s[38:39] offset:3072
	s_add_u32 s36, s36, 0x1800
	s_addc_u32 s37, s37, 0
	s_add_u32 s38, s38, 0x1800
	s_addc_u32 s39, s39, 0
	global_load_dword v10, v40, s[36:37]
	global_load_dword v30, v40, s[38:39]
	global_load_dword v11, v40, s[36:37] offset:3072
	global_load_dword v31, v40, s[38:39] offset:3072
	s_add_u32 s36, s36, 0x1800
	s_addc_u32 s37, s37, 0
	s_add_u32 s38, s38, 0x1800
	s_addc_u32 s39, s39, 0
	global_load_dword v12, v40, s[36:37]
	global_load_dword v32, v40, s[38:39]
	global_load_dword v13, v40, s[36:37] offset:3072
	global_load_dword v33, v40, s[38:39] offset:3072
	s_add_u32 s36, s36, 0x1800
	s_addc_u32 s37, s37, 0
	s_add_u32 s38, s38, 0x1800
	s_addc_u32 s39, s39, 0
	global_load_dword v14, v40, s[36:37]
	global_load_dword v34, v40, s[38:39]
	global_load_dword v15, v40, s[36:37] offset:3072
	global_load_dword v35, v40, s[38:39] offset:3072
	s_add_u32 s36, s36, 0x1800
	s_addc_u32 s37, s37, 0
	s_add_u32 s38, s38, 0x1800
	s_addc_u32 s39, s39, 0
	global_load_dword v16, v40, s[36:37]
	global_load_dword v36, v40, s[38:39]
	global_load_dword v17, v40, s[36:37] offset:3072
	global_load_dword v37, v40, s[38:39] offset:3072
	s_add_u32 s36, s36, 0x1800
	s_addc_u32 s37, s37, 0
	s_add_u32 s38, s38, 0x1800
	s_addc_u32 s39, s39, 0
	global_load_dword v18, v40, s[36:37]
	global_load_dword v38, v40, s[38:39]
	global_load_dword v19, v40, s[36:37] offset:3072
	global_load_dword v39, v40, s[38:39] offset:3072
	s_add_u32 s36, s36, 0x1800
	s_addc_u32 s37, s37, 0
	s_add_u32 s38, s38, 0x1800
	s_addc_u32 s39, s39, 0
	s_waitcnt vmcnt(30)
	v_mul_f32_e32 v21, v21, v4
	v_fma_f32 v20, v20, v4, v24
	s_waitcnt vmcnt(28)
	v_mul_f32_e32 v21, v21, v5
	v_fma_f32 v20, v20, v5, v25
	s_waitcnt vmcnt(26)
	v_mul_f32_e32 v21, v21, v6
	v_fma_f32 v20, v20, v6, v26
	s_waitcnt vmcnt(24)
	v_mul_f32_e32 v21, v21, v7
	v_fma_f32 v20, v20, v7, v27
	s_waitcnt vmcnt(22)
	v_mul_f32_e32 v21, v21, v8
	v_fma_f32 v20, v20, v8, v28
	s_waitcnt vmcnt(20)
	v_mul_f32_e32 v21, v21, v9
	v_fma_f32 v20, v20, v9, v29
	s_waitcnt vmcnt(18)
	v_mul_f32_e32 v21, v21, v10
	v_fma_f32 v20, v20, v10, v30
	s_waitcnt vmcnt(16)
	v_mul_f32_e32 v21, v21, v11
	v_fma_f32 v20, v20, v11, v31
	s_waitcnt vmcnt(14)
	v_mul_f32_e32 v21, v21, v12
	v_fma_f32 v20, v20, v12, v32
	s_waitcnt vmcnt(12)
	v_mul_f32_e32 v21, v21, v13
	v_fma_f32 v20, v20, v13, v33
	s_waitcnt vmcnt(10)
	v_mul_f32_e32 v21, v21, v14
	v_fma_f32 v20, v20, v14, v34
	s_waitcnt vmcnt(8)
	v_mul_f32_e32 v21, v21, v15
	v_fma_f32 v20, v20, v15, v35
	s_waitcnt vmcnt(6)
	v_mul_f32_e32 v21, v21, v16
	v_fma_f32 v20, v20, v16, v36
	s_waitcnt vmcnt(4)
	v_mul_f32_e32 v21, v21, v17
	v_fma_f32 v20, v20, v17, v37
	s_waitcnt vmcnt(2)
	v_mul_f32_e32 v21, v21, v18
	v_fma_f32 v20, v20, v18, v38
	s_waitcnt vmcnt(0)
	v_mul_f32_e32 v21, v21, v19
	v_fma_f32 v20, v20, v19, v39
	s_sub_i32 s12, s12, 1
	s_cmp_lg_u32 s12, 0
	s_cbranch_scc1 .Llru_scan_16
.Llru_scan_done:
.LBB0_1267:
	s_or_b64 exec, exec, s[28:29]
	s_movk_i32 s10, 0x80
	v_lshl_add_u32 v6, v2, 2, 0
	v_cmp_gt_i32_e64 s[28:29], s10, v2
	ds_write2st64_b32 v6, v21, v20 offset1:8
	s_waitcnt lgkmcnt(0)
	s_barrier
	s_and_saveexec_b64 s[34:35], s[28:29]
	s_cbranch_execz .LBB0_1269
	ds_read2st64_b32 v[4:5], v6 offset1:2
	ds_read2st64_b32 v[8:9], v6 offset0:8 offset1:10
	s_waitcnt lgkmcnt(0)
	v_fma_f32 v0, 0, v4, v8
	v_fmac_f32_e32 v9, v0, v5
	ds_read2st64_b32 v[4:5], v6 offset0:4 offset1:6
	ds_read2st64_b32 v[10:11], v6 offset0:12 offset1:14
	s_waitcnt lgkmcnt(0)
	v_fma_f32 v0, v9, v4, v10
	v_fmac_f32_e32 v11, v0, v5
	ds_write_b32 v6, v11 offset:4096
